# GEMM K loops: per-segment s_setprio flips deleted, one static s_setprio 1 for waves 0-3 (older half) before each K loop
# speedup vs baseline: 1.0105x; 1.0090x over previous
.LBB0_310:
	s_ashr_i32 s55, s54, 31
	s_lshl_b64 s[58:59], s[54:55], 19
	s_add_u32 s58, s29, s58
	s_addc_u32 s59, s30, s59
	s_and_b64 s[60:61], s[38:39], exec
	s_cselect_b32 s33, s59, s35
	s_cselect_b32 s36, s58, s34
	s_ashr_i32 s53, s52, 31
	s_lshl_b64 s[60:61], s[52:53], 19
	s_add_u32 s60, s45, s60
	s_addc_u32 s61, s66, s61
	s_and_b64 s[62:63], s[38:39], exec
	s_cselect_b32 s53, s61, s65
	s_cselect_b32 s55, s60, s64
	s_add_u32 s62, s34, 0x40080
	s_addc_u32 s63, s35, 0
	s_add_u32 s75, s64, 0x100
	v_mov_b32_e32 v0, 0
	s_addc_u32 s79, s65, 0
	s_mov_b32 s82, -2
	v_mov_b32_e32 v1, v0
	v_mov_b32_e32 v2, v0
	v_mov_b32_e32 v3, v0
	v_mov_b32_e32 v4, v0
	v_mov_b32_e32 v5, v0
	v_mov_b32_e32 v6, v0
	v_mov_b32_e32 v7, v0
	v_mov_b32_e32 v16, v0
	v_mov_b32_e32 v17, v0
	v_mov_b32_e32 v18, v0
	v_mov_b32_e32 v19, v0
	v_mov_b32_e32 v20, v0
	v_mov_b32_e32 v21, v0
	v_mov_b32_e32 v22, v0
	v_mov_b32_e32 v23, v0
	v_mov_b32_e32 v32, v0
	v_mov_b32_e32 v33, v0
	v_mov_b32_e32 v34, v0
	v_mov_b32_e32 v35, v0
	v_mov_b32_e32 v36, v0
	v_mov_b32_e32 v37, v0
	v_mov_b32_e32 v38, v0
	v_mov_b32_e32 v39, v0
	v_mov_b32_e32 v48, v0
	v_mov_b32_e32 v49, v0
	v_mov_b32_e32 v50, v0
	v_mov_b32_e32 v51, v0
	v_mov_b32_e32 v52, v0
	v_mov_b32_e32 v53, v0
	v_mov_b32_e32 v54, v0
	v_mov_b32_e32 v55, v0
	v_mov_b32_e32 v8, v0
	v_mov_b32_e32 v9, v0
	v_mov_b32_e32 v10, v0
	v_mov_b32_e32 v11, v0
	v_mov_b32_e32 v12, v0
	v_mov_b32_e32 v13, v0
	v_mov_b32_e32 v14, v0
	v_mov_b32_e32 v15, v0
	v_mov_b32_e32 v24, v0
	v_mov_b32_e32 v25, v0
	v_mov_b32_e32 v26, v0
	v_mov_b32_e32 v27, v0
	v_mov_b32_e32 v28, v0
	v_mov_b32_e32 v29, v0
	v_mov_b32_e32 v30, v0
	v_mov_b32_e32 v31, v0
	v_mov_b32_e32 v40, v0
	v_mov_b32_e32 v41, v0
	v_mov_b32_e32 v42, v0
	v_mov_b32_e32 v43, v0
	v_mov_b32_e32 v44, v0
	v_mov_b32_e32 v45, v0
	v_mov_b32_e32 v46, v0
	v_mov_b32_e32 v47, v0
	v_mov_b32_e32 v56, v0
	v_mov_b32_e32 v57, v0
	v_mov_b32_e32 v58, v0
	v_mov_b32_e32 v59, v0
	v_mov_b32_e32 v60, v0
	v_mov_b32_e32 v61, v0
	v_mov_b32_e32 v62, v0
	v_mov_b32_e32 v63, v0
	v_mov_b32_e32 v64, v0
	v_mov_b32_e32 v65, v0
	v_mov_b32_e32 v66, v0
	v_mov_b32_e32 v67, v0
	v_mov_b32_e32 v68, v0
	v_mov_b32_e32 v69, v0
	v_mov_b32_e32 v70, v0
	v_mov_b32_e32 v71, v0
	v_mov_b32_e32 v80, v0
	v_mov_b32_e32 v81, v0
	v_mov_b32_e32 v82, v0
	v_mov_b32_e32 v83, v0
	v_mov_b32_e32 v84, v0
	v_mov_b32_e32 v85, v0
	v_mov_b32_e32 v86, v0
	v_mov_b32_e32 v87, v0
	v_mov_b32_e32 v96, v0
	v_mov_b32_e32 v97, v0
	v_mov_b32_e32 v98, v0
	v_mov_b32_e32 v99, v0
	v_mov_b32_e32 v100, v0
	v_mov_b32_e32 v101, v0
	v_mov_b32_e32 v102, v0
	v_mov_b32_e32 v103, v0
	v_mov_b32_e32 v112, v0
	v_mov_b32_e32 v113, v0
	v_mov_b32_e32 v114, v0
	v_mov_b32_e32 v115, v0
	v_mov_b32_e32 v116, v0
	v_mov_b32_e32 v117, v0
	v_mov_b32_e32 v118, v0
	v_mov_b32_e32 v119, v0
	v_mov_b32_e32 v72, v0
	v_mov_b32_e32 v73, v0
	v_mov_b32_e32 v74, v0
	v_mov_b32_e32 v75, v0
	v_mov_b32_e32 v76, v0
	v_mov_b32_e32 v77, v0
	v_mov_b32_e32 v78, v0
	v_mov_b32_e32 v79, v0
	v_mov_b32_e32 v88, v0
	v_mov_b32_e32 v89, v0
	v_mov_b32_e32 v90, v0
	v_mov_b32_e32 v91, v0
	v_mov_b32_e32 v92, v0
	v_mov_b32_e32 v93, v0
	v_mov_b32_e32 v94, v0
	v_mov_b32_e32 v95, v0
	v_mov_b32_e32 v104, v0
	v_mov_b32_e32 v105, v0
	v_mov_b32_e32 v106, v0
	v_mov_b32_e32 v107, v0
	v_mov_b32_e32 v108, v0
	v_mov_b32_e32 v109, v0
	v_mov_b32_e32 v110, v0
	v_mov_b32_e32 v111, v0
	v_mov_b32_e32 v120, v0
	v_mov_b32_e32 v121, v0
	v_mov_b32_e32 v122, v0
	v_mov_b32_e32 v123, v0
	v_mov_b32_e32 v124, v0
	v_mov_b32_e32 v125, v0
	v_mov_b32_e32 v126, v0
	v_mov_b32_e32 v127, v0
	v_readfirstlane_b32 s4, v182
	s_nop 3
	s_cmp_lt_u32 s4, 256
	s_cbranch_scc0 .Lkprio_311
	s_setprio 1

.LBB0_405:
	s_add_u32 s3, s62, 0x100
	v_mov_b32_e32 v0, 0
	s_addc_u32 s28, s63, 0
	s_mov_b32 s29, -2
	s_waitcnt lgkmcnt(0)
	v_mov_b32_e32 v1, v0
	v_mov_b32_e32 v2, v0
	v_mov_b32_e32 v3, v0
	v_mov_b32_e32 v4, v0
	v_mov_b32_e32 v5, v0
	v_mov_b32_e32 v6, v0
	v_mov_b32_e32 v7, v0
	v_mov_b32_e32 v16, v0
	v_mov_b32_e32 v17, v0
	v_mov_b32_e32 v18, v0
	v_mov_b32_e32 v19, v0
	v_mov_b32_e32 v20, v0
	v_mov_b32_e32 v21, v0
	v_mov_b32_e32 v22, v0
	v_mov_b32_e32 v23, v0
	v_mov_b32_e32 v32, v0
	v_mov_b32_e32 v33, v0
	v_mov_b32_e32 v34, v0
	v_mov_b32_e32 v35, v0
	v_mov_b32_e32 v36, v0
	v_mov_b32_e32 v37, v0
	v_mov_b32_e32 v38, v0
	v_mov_b32_e32 v39, v0
	v_mov_b32_e32 v48, v0
	v_mov_b32_e32 v49, v0
	v_mov_b32_e32 v50, v0
	v_mov_b32_e32 v51, v0
	v_mov_b32_e32 v52, v0
	v_mov_b32_e32 v53, v0
	v_mov_b32_e32 v54, v0
	v_mov_b32_e32 v55, v0
	v_mov_b32_e32 v8, v0
	v_mov_b32_e32 v9, v0
	v_mov_b32_e32 v10, v0
	v_mov_b32_e32 v11, v0
	v_mov_b32_e32 v12, v0
	v_mov_b32_e32 v13, v0
	v_mov_b32_e32 v14, v0
	v_mov_b32_e32 v15, v0
	v_mov_b32_e32 v24, v0
	v_mov_b32_e32 v25, v0
	v_mov_b32_e32 v26, v0
	v_mov_b32_e32 v27, v0
	v_mov_b32_e32 v28, v0
	v_mov_b32_e32 v29, v0
	v_mov_b32_e32 v30, v0
	v_mov_b32_e32 v31, v0
	v_mov_b32_e32 v40, v0
	v_mov_b32_e32 v41, v0
	v_mov_b32_e32 v42, v0
	v_mov_b32_e32 v43, v0
	v_mov_b32_e32 v44, v0
	v_mov_b32_e32 v45, v0
	v_mov_b32_e32 v46, v0
	v_mov_b32_e32 v47, v0
	v_mov_b32_e32 v56, v0
	v_mov_b32_e32 v57, v0
	v_mov_b32_e32 v58, v0
	v_mov_b32_e32 v59, v0
	v_mov_b32_e32 v60, v0
	v_mov_b32_e32 v61, v0
	v_mov_b32_e32 v62, v0
	v_mov_b32_e32 v63, v0
	v_mov_b32_e32 v64, v0
	v_mov_b32_e32 v65, v0
	v_mov_b32_e32 v66, v0
	v_mov_b32_e32 v67, v0
	v_mov_b32_e32 v68, v0
	v_mov_b32_e32 v69, v0
	v_mov_b32_e32 v70, v0
	v_mov_b32_e32 v71, v0
	v_mov_b32_e32 v80, v0
	v_mov_b32_e32 v81, v0
	v_mov_b32_e32 v82, v0
	v_mov_b32_e32 v83, v0
	v_mov_b32_e32 v84, v0
	v_mov_b32_e32 v85, v0
	v_mov_b32_e32 v86, v0
	v_mov_b32_e32 v87, v0
	v_mov_b32_e32 v96, v0
	v_mov_b32_e32 v97, v0
	v_mov_b32_e32 v98, v0
	v_mov_b32_e32 v99, v0
	v_mov_b32_e32 v100, v0
	v_mov_b32_e32 v101, v0
	v_mov_b32_e32 v102, v0
	v_mov_b32_e32 v103, v0
	v_mov_b32_e32 v112, v0
	v_mov_b32_e32 v113, v0
	v_mov_b32_e32 v114, v0
	v_mov_b32_e32 v115, v0
	v_mov_b32_e32 v116, v0
	v_mov_b32_e32 v117, v0
	v_mov_b32_e32 v118, v0
	v_mov_b32_e32 v119, v0
	v_mov_b32_e32 v72, v0
	v_mov_b32_e32 v73, v0
	v_mov_b32_e32 v74, v0
	v_mov_b32_e32 v75, v0
	v_mov_b32_e32 v76, v0
	v_mov_b32_e32 v77, v0
	v_mov_b32_e32 v78, v0
	v_mov_b32_e32 v79, v0
	v_mov_b32_e32 v88, v0
	v_mov_b32_e32 v89, v0
	v_mov_b32_e32 v90, v0
	v_mov_b32_e32 v91, v0
	v_mov_b32_e32 v92, v0
	v_mov_b32_e32 v93, v0
	v_mov_b32_e32 v94, v0
	v_mov_b32_e32 v95, v0
	v_mov_b32_e32 v104, v0
	v_mov_b32_e32 v105, v0
	v_mov_b32_e32 v106, v0
	v_mov_b32_e32 v107, v0
	v_mov_b32_e32 v108, v0
	v_mov_b32_e32 v109, v0
	v_mov_b32_e32 v110, v0
	v_mov_b32_e32 v111, v0
	v_mov_b32_e32 v120, v0
	v_mov_b32_e32 v121, v0
	v_mov_b32_e32 v122, v0
	v_mov_b32_e32 v123, v0
	v_mov_b32_e32 v124, v0
	v_mov_b32_e32 v125, v0
	v_mov_b32_e32 v126, v0
	v_mov_b32_e32 v127, v0
	v_readfirstlane_b32 s4, v182
	s_nop 3
	s_cmp_lt_u32 s4, 256
	s_cbranch_scc0 .Lkprio_406
	s_setprio 1

.LBB0_455:
	s_add_u32 s28, s60, 0x100
	v_mov_b32_e32 v0, 0
	s_addc_u32 s29, s61, 0
	s_mov_b32 s51, -2
	s_waitcnt lgkmcnt(0)
	v_mov_b32_e32 v1, v0
	v_mov_b32_e32 v2, v0
	v_mov_b32_e32 v3, v0
	v_mov_b32_e32 v4, v0
	v_mov_b32_e32 v5, v0
	v_mov_b32_e32 v6, v0
	v_mov_b32_e32 v7, v0
	v_mov_b32_e32 v16, v0
	v_mov_b32_e32 v17, v0
	v_mov_b32_e32 v18, v0
	v_mov_b32_e32 v19, v0
	v_mov_b32_e32 v20, v0
	v_mov_b32_e32 v21, v0
	v_mov_b32_e32 v22, v0
	v_mov_b32_e32 v23, v0
	v_mov_b32_e32 v32, v0
	v_mov_b32_e32 v33, v0
	v_mov_b32_e32 v34, v0
	v_mov_b32_e32 v35, v0
	v_mov_b32_e32 v36, v0
	v_mov_b32_e32 v37, v0
	v_mov_b32_e32 v38, v0
	v_mov_b32_e32 v39, v0
	v_mov_b32_e32 v48, v0
	v_mov_b32_e32 v49, v0
	v_mov_b32_e32 v50, v0
	v_mov_b32_e32 v51, v0
	v_mov_b32_e32 v52, v0
	v_mov_b32_e32 v53, v0
	v_mov_b32_e32 v54, v0
	v_mov_b32_e32 v55, v0
	v_mov_b32_e32 v8, v0
	v_mov_b32_e32 v9, v0
	v_mov_b32_e32 v10, v0
	v_mov_b32_e32 v11, v0
	v_mov_b32_e32 v12, v0
	v_mov_b32_e32 v13, v0
	v_mov_b32_e32 v14, v0
	v_mov_b32_e32 v15, v0
	v_mov_b32_e32 v24, v0
	v_mov_b32_e32 v25, v0
	v_mov_b32_e32 v26, v0
	v_mov_b32_e32 v27, v0
	v_mov_b32_e32 v28, v0
	v_mov_b32_e32 v29, v0
	v_mov_b32_e32 v30, v0
	v_mov_b32_e32 v31, v0
	v_mov_b32_e32 v40, v0
	v_mov_b32_e32 v41, v0
	v_mov_b32_e32 v42, v0
	v_mov_b32_e32 v43, v0
	v_mov_b32_e32 v44, v0
	v_mov_b32_e32 v45, v0
	v_mov_b32_e32 v46, v0
	v_mov_b32_e32 v47, v0
	v_mov_b32_e32 v56, v0
	v_mov_b32_e32 v57, v0
	v_mov_b32_e32 v58, v0
	v_mov_b32_e32 v59, v0
	v_mov_b32_e32 v60, v0
	v_mov_b32_e32 v61, v0
	v_mov_b32_e32 v62, v0
	v_mov_b32_e32 v63, v0
	v_mov_b32_e32 v64, v0
	v_mov_b32_e32 v65, v0
	v_mov_b32_e32 v66, v0
	v_mov_b32_e32 v67, v0
	v_mov_b32_e32 v68, v0
	v_mov_b32_e32 v69, v0
	v_mov_b32_e32 v70, v0
	v_mov_b32_e32 v71, v0
	v_mov_b32_e32 v80, v0
	v_mov_b32_e32 v81, v0
	v_mov_b32_e32 v82, v0
	v_mov_b32_e32 v83, v0
	v_mov_b32_e32 v84, v0
	v_mov_b32_e32 v85, v0
	v_mov_b32_e32 v86, v0
	v_mov_b32_e32 v87, v0
	v_mov_b32_e32 v96, v0
	v_mov_b32_e32 v97, v0
	v_mov_b32_e32 v98, v0
	v_mov_b32_e32 v99, v0
	v_mov_b32_e32 v100, v0
	v_mov_b32_e32 v101, v0
	v_mov_b32_e32 v102, v0
	v_mov_b32_e32 v103, v0
	v_mov_b32_e32 v112, v0
	v_mov_b32_e32 v113, v0
	v_mov_b32_e32 v114, v0
	v_mov_b32_e32 v115, v0
	v_mov_b32_e32 v116, v0
	v_mov_b32_e32 v117, v0
	v_mov_b32_e32 v118, v0
	v_mov_b32_e32 v119, v0
	v_mov_b32_e32 v72, v0
	v_mov_b32_e32 v73, v0
	v_mov_b32_e32 v74, v0
	v_mov_b32_e32 v75, v0
	v_mov_b32_e32 v76, v0
	v_mov_b32_e32 v77, v0
	v_mov_b32_e32 v78, v0
	v_mov_b32_e32 v79, v0
	v_mov_b32_e32 v88, v0
	v_mov_b32_e32 v89, v0
	v_mov_b32_e32 v90, v0
	v_mov_b32_e32 v91, v0
	v_mov_b32_e32 v92, v0
	v_mov_b32_e32 v93, v0
	v_mov_b32_e32 v94, v0
	v_mov_b32_e32 v95, v0
	v_mov_b32_e32 v104, v0
	v_mov_b32_e32 v105, v0
	v_mov_b32_e32 v106, v0
	v_mov_b32_e32 v107, v0
	v_mov_b32_e32 v108, v0
	v_mov_b32_e32 v109, v0
	v_mov_b32_e32 v110, v0
	v_mov_b32_e32 v111, v0
	v_mov_b32_e32 v120, v0
	v_mov_b32_e32 v121, v0
	v_mov_b32_e32 v122, v0
	v_mov_b32_e32 v123, v0
	v_mov_b32_e32 v124, v0
	v_mov_b32_e32 v125, v0
	v_mov_b32_e32 v126, v0
	v_mov_b32_e32 v127, v0
	v_readfirstlane_b32 s4, v182
	s_nop 3
	s_cmp_lt_u32 s4, 256
	s_cbranch_scc0 .Lkprio_456
	s_setprio 1

.LBB0_604:
	s_ashr_i32 s71, s70, 31
	s_lshl_b64 s[34:35], s[70:71], 19
	s_cmp_eq_u32 s30, 0
	s_cselect_b32 s4, s29, s55
	s_cselect_b32 s3, s47, s46
	s_cselect_b32 s5, s53, s29
	s_cselect_b32 s71, s54, s47
	s_add_u32 s72, s4, s34
	s_addc_u32 s73, s3, s35
	s_and_b64 s[34:35], s[40:41], exec
	s_cselect_b32 s3, s73, s1
	s_cselect_b32 s36, s72, s0
	s_ashr_i32 s39, s38, 31
	s_lshl_b64 s[34:35], s[38:39], 19
	s_add_u32 s74, s5, s34
	s_addc_u32 s75, s71, s35
	s_and_b64 s[34:35], s[40:41], exec
	s_cselect_b32 s39, s75, s43
	s_cselect_b32 s71, s74, s42
	s_add_u32 s0, s0, 0x40080
	s_addc_u32 s1, s1, 0
	s_add_u32 s79, s42, 0x100
	v_mov_b32_e32 v0, 0
	s_addc_u32 s84, s43, 0
	s_mov_b32 s88, -2
	v_mov_b32_e32 v1, v0
	v_mov_b32_e32 v2, v0
	v_mov_b32_e32 v3, v0
	v_mov_b32_e32 v4, v0
	v_mov_b32_e32 v5, v0
	v_mov_b32_e32 v6, v0
	v_mov_b32_e32 v7, v0
	v_mov_b32_e32 v8, v0
	v_mov_b32_e32 v9, v0
	v_mov_b32_e32 v10, v0
	v_mov_b32_e32 v11, v0
	v_mov_b32_e32 v16, v0
	v_mov_b32_e32 v17, v0
	v_mov_b32_e32 v18, v0
	v_mov_b32_e32 v19, v0
	v_mov_b32_e32 v24, v0
	v_mov_b32_e32 v25, v0
	v_mov_b32_e32 v26, v0
	v_mov_b32_e32 v27, v0
	v_mov_b32_e32 v32, v0
	v_mov_b32_e32 v33, v0
	v_mov_b32_e32 v34, v0
	v_mov_b32_e32 v35, v0
	v_mov_b32_e32 v40, v0
	v_mov_b32_e32 v41, v0
	v_mov_b32_e32 v42, v0
	v_mov_b32_e32 v43, v0
	v_mov_b32_e32 v48, v0
	v_mov_b32_e32 v49, v0
	v_mov_b32_e32 v50, v0
	v_mov_b32_e32 v51, v0
	v_mov_b32_e32 v12, v0
	v_mov_b32_e32 v13, v0
	v_mov_b32_e32 v14, v0
	v_mov_b32_e32 v15, v0
	v_mov_b32_e32 v20, v0
	v_mov_b32_e32 v21, v0
	v_mov_b32_e32 v22, v0
	v_mov_b32_e32 v23, v0
	v_mov_b32_e32 v28, v0
	v_mov_b32_e32 v29, v0
	v_mov_b32_e32 v30, v0
	v_mov_b32_e32 v31, v0
	v_mov_b32_e32 v36, v0
	v_mov_b32_e32 v37, v0
	v_mov_b32_e32 v38, v0
	v_mov_b32_e32 v39, v0
	v_mov_b32_e32 v44, v0
	v_mov_b32_e32 v45, v0
	v_mov_b32_e32 v46, v0
	v_mov_b32_e32 v47, v0
	v_mov_b32_e32 v52, v0
	v_mov_b32_e32 v53, v0
	v_mov_b32_e32 v54, v0
	v_mov_b32_e32 v55, v0
	v_mov_b32_e32 v56, v0
	v_mov_b32_e32 v57, v0
	v_mov_b32_e32 v58, v0
	v_mov_b32_e32 v59, v0
	v_mov_b32_e32 v60, v0
	v_mov_b32_e32 v61, v0
	v_mov_b32_e32 v62, v0
	v_mov_b32_e32 v63, v0
	v_mov_b32_e32 v64, v0
	v_mov_b32_e32 v65, v0
	v_mov_b32_e32 v66, v0
	v_mov_b32_e32 v67, v0
	v_mov_b32_e32 v68, v0
	v_mov_b32_e32 v69, v0
	v_mov_b32_e32 v70, v0
	v_mov_b32_e32 v71, v0
	v_mov_b32_e32 v72, v0
	v_mov_b32_e32 v73, v0
	v_mov_b32_e32 v74, v0
	v_mov_b32_e32 v75, v0
	v_mov_b32_e32 v80, v0
	v_mov_b32_e32 v81, v0
	v_mov_b32_e32 v82, v0
	v_mov_b32_e32 v83, v0
	v_mov_b32_e32 v88, v0
	v_mov_b32_e32 v89, v0
	v_mov_b32_e32 v90, v0
	v_mov_b32_e32 v91, v0
	v_mov_b32_e32 v96, v0
	v_mov_b32_e32 v97, v0
	v_mov_b32_e32 v98, v0
	v_mov_b32_e32 v99, v0
	v_mov_b32_e32 v104, v0
	v_mov_b32_e32 v105, v0
	v_mov_b32_e32 v106, v0
	v_mov_b32_e32 v107, v0
	v_mov_b32_e32 v116, v0
	v_mov_b32_e32 v117, v0
	v_mov_b32_e32 v118, v0
	v_mov_b32_e32 v119, v0
	v_mov_b32_e32 v76, v0
	v_mov_b32_e32 v77, v0
	v_mov_b32_e32 v78, v0
	v_mov_b32_e32 v79, v0
	v_mov_b32_e32 v84, v0
	v_mov_b32_e32 v85, v0
	v_mov_b32_e32 v86, v0
	v_mov_b32_e32 v87, v0
	v_mov_b32_e32 v92, v0
	v_mov_b32_e32 v93, v0
	v_mov_b32_e32 v94, v0
	v_mov_b32_e32 v95, v0
	v_mov_b32_e32 v100, v0
	v_mov_b32_e32 v101, v0
	v_mov_b32_e32 v102, v0
	v_mov_b32_e32 v103, v0
	v_mov_b32_e32 v108, v0
	v_mov_b32_e32 v109, v0
	v_mov_b32_e32 v110, v0
	v_mov_b32_e32 v111, v0
	v_mov_b32_e32 v112, v0
	v_mov_b32_e32 v113, v0
	v_mov_b32_e32 v114, v0
	v_mov_b32_e32 v115, v0
	v_mov_b32_e32 v120, v0
	v_mov_b32_e32 v121, v0
	v_mov_b32_e32 v122, v0
	v_mov_b32_e32 v123, v0
	v_mov_b32_e32 v124, v0
	v_mov_b32_e32 v125, v0
	v_mov_b32_e32 v126, v0
	v_mov_b32_e32 v127, v0
	v_readfirstlane_b32 s4, v182
	s_nop 3
	s_cmp_lt_u32 s4, 256
	s_cbranch_scc0 .Lkprio_605
	s_setprio 1

.LBB0_1004:
	s_ashr_i32 s47, s46, 31
	s_lshl_b64 s[4:5], s[46:47], 18
	s_add_u32 s48, s33, s4
	s_addc_u32 s49, s36, s5
	s_and_b64 s[4:5], s[38:39], exec
	s_cselect_b32 s29, s49, s55
	s_cselect_b32 s47, s48, s54
	s_ashr_i32 s45, s44, 31
	s_lshl_b64 s[4:5], s[44:45], 18
	s_add_u32 s50, s60, s4
	s_addc_u32 s51, s61, s5
	s_and_b64 s[4:5], s[38:39], exec
	s_cselect_b32 s45, s51, s59
	s_cselect_b32 s68, s50, s58
	s_add_u32 s54, s54, 0x20080
	s_addc_u32 s55, s55, 0
	s_add_u32 s69, s58, 0x100
	v_mov_b32_e32 v4, 0
	s_addc_u32 s70, s59, 0
	s_mov_b32 s71, -2
	v_mov_b32_e32 v5, v4
	v_mov_b32_e32 v6, v4
	v_mov_b32_e32 v7, v4
	v_mov_b32_e32 v0, v4
	v_mov_b32_e32 v1, v4
	v_mov_b32_e32 v2, v4
	v_mov_b32_e32 v3, v4
	v_mov_b32_e32 v20, v4
	v_mov_b32_e32 v21, v4
	v_mov_b32_e32 v22, v4
	v_mov_b32_e32 v23, v4
	v_mov_b32_e32 v16, v4
	v_mov_b32_e32 v17, v4
	v_mov_b32_e32 v18, v4
	v_mov_b32_e32 v19, v4
	v_mov_b32_e32 v36, v4
	v_mov_b32_e32 v37, v4
	v_mov_b32_e32 v38, v4
	v_mov_b32_e32 v39, v4
	v_mov_b32_e32 v32, v4
	v_mov_b32_e32 v33, v4
	v_mov_b32_e32 v34, v4
	v_mov_b32_e32 v35, v4
	v_mov_b32_e32 v52, v4
	v_mov_b32_e32 v53, v4
	v_mov_b32_e32 v54, v4
	v_mov_b32_e32 v55, v4
	v_mov_b32_e32 v48, v4
	v_mov_b32_e32 v49, v4
	v_mov_b32_e32 v50, v4
	v_mov_b32_e32 v51, v4
	v_mov_b32_e32 v12, v4
	v_mov_b32_e32 v13, v4
	v_mov_b32_e32 v14, v4
	v_mov_b32_e32 v15, v4
	v_mov_b32_e32 v8, v4
	v_mov_b32_e32 v9, v4
	v_mov_b32_e32 v10, v4
	v_mov_b32_e32 v11, v4
	v_mov_b32_e32 v28, v4
	v_mov_b32_e32 v29, v4
	v_mov_b32_e32 v30, v4
	v_mov_b32_e32 v31, v4
	v_mov_b32_e32 v24, v4
	v_mov_b32_e32 v25, v4
	v_mov_b32_e32 v26, v4
	v_mov_b32_e32 v27, v4
	v_mov_b32_e32 v44, v4
	v_mov_b32_e32 v45, v4
	v_mov_b32_e32 v46, v4
	v_mov_b32_e32 v47, v4
	v_mov_b32_e32 v40, v4
	v_mov_b32_e32 v41, v4
	v_mov_b32_e32 v42, v4
	v_mov_b32_e32 v43, v4
	v_mov_b32_e32 v60, v4
	v_mov_b32_e32 v61, v4
	v_mov_b32_e32 v62, v4
	v_mov_b32_e32 v63, v4
	v_mov_b32_e32 v56, v4
	v_mov_b32_e32 v57, v4
	v_mov_b32_e32 v58, v4
	v_mov_b32_e32 v59, v4
	v_mov_b32_e32 v68, v4
	v_mov_b32_e32 v69, v4
	v_mov_b32_e32 v70, v4
	v_mov_b32_e32 v71, v4
	v_mov_b32_e32 v64, v4
	v_mov_b32_e32 v65, v4
	v_mov_b32_e32 v66, v4
	v_mov_b32_e32 v67, v4
	v_mov_b32_e32 v84, v4
	v_mov_b32_e32 v85, v4
	v_mov_b32_e32 v86, v4
	v_mov_b32_e32 v87, v4
	v_mov_b32_e32 v80, v4
	v_mov_b32_e32 v81, v4
	v_mov_b32_e32 v82, v4
	v_mov_b32_e32 v83, v4
	v_mov_b32_e32 v100, v4
	v_mov_b32_e32 v101, v4
	v_mov_b32_e32 v102, v4
	v_mov_b32_e32 v103, v4
	v_mov_b32_e32 v96, v4
	v_mov_b32_e32 v97, v4
	v_mov_b32_e32 v98, v4
	v_mov_b32_e32 v99, v4
	v_mov_b32_e32 v116, v4
	v_mov_b32_e32 v117, v4
	v_mov_b32_e32 v118, v4
	v_mov_b32_e32 v119, v4
	v_mov_b32_e32 v112, v4
	v_mov_b32_e32 v113, v4
	v_mov_b32_e32 v114, v4
	v_mov_b32_e32 v115, v4
	v_mov_b32_e32 v76, v4
	v_mov_b32_e32 v77, v4
	v_mov_b32_e32 v78, v4
	v_mov_b32_e32 v79, v4
	v_mov_b32_e32 v72, v4
	v_mov_b32_e32 v73, v4
	v_mov_b32_e32 v74, v4
	v_mov_b32_e32 v75, v4
	v_mov_b32_e32 v92, v4
	v_mov_b32_e32 v93, v4
	v_mov_b32_e32 v94, v4
	v_mov_b32_e32 v95, v4
	v_mov_b32_e32 v88, v4
	v_mov_b32_e32 v89, v4
	v_mov_b32_e32 v90, v4
	v_mov_b32_e32 v91, v4
	v_mov_b32_e32 v108, v4
	v_mov_b32_e32 v109, v4
	v_mov_b32_e32 v110, v4
	v_mov_b32_e32 v111, v4
	v_mov_b32_e32 v104, v4
	v_mov_b32_e32 v105, v4
	v_mov_b32_e32 v106, v4
	v_mov_b32_e32 v107, v4
	v_mov_b32_e32 v124, v4
	v_mov_b32_e32 v125, v4
	v_mov_b32_e32 v126, v4
	v_mov_b32_e32 v127, v4
	v_mov_b32_e32 v120, v4
	v_mov_b32_e32 v121, v4
	v_mov_b32_e32 v122, v4
	v_mov_b32_e32 v123, v4
	v_readfirstlane_b32 s4, v182
	s_nop 3
	s_cmp_lt_u32 s4, 256
	s_cbranch_scc0 .Lkprio_1005
	s_setprio 1

.LBB0_1092:
	s_ashr_i32 s51, s50, 31
	s_lshl_b64 s[4:5], s[50:51], 18
	s_add_u32 s52, s29, s4
	s_addc_u32 s53, s30, s5
	s_and_b64 s[4:5], s[38:39], exec
	s_cselect_b32 s33, s53, s59
	s_cselect_b32 s36, s52, s58
	s_ashr_i32 s49, s48, 31
	s_lshl_b64 s[4:5], s[48:49], 18
	s_add_u32 s54, s62, s4
	s_addc_u32 s55, s63, s5
	s_and_b64 s[4:5], s[38:39], exec
	s_cselect_b32 s49, s55, s61
	s_cselect_b32 s51, s54, s60
	s_add_u32 s58, s58, 0x20080
	s_addc_u32 s59, s59, 0
	s_add_u32 s71, s60, 0x100
	v_mov_b32_e32 v0, 0
	s_addc_u32 s72, s61, 0
	s_mov_b32 s73, -2
	v_mov_b32_e32 v1, v0
	v_mov_b32_e32 v2, v0
	v_mov_b32_e32 v3, v0
	v_mov_b32_e32 v4, v0
	v_mov_b32_e32 v5, v0
	v_mov_b32_e32 v6, v0
	v_mov_b32_e32 v7, v0
	v_mov_b32_e32 v16, v0
	v_mov_b32_e32 v17, v0
	v_mov_b32_e32 v18, v0
	v_mov_b32_e32 v19, v0
	v_mov_b32_e32 v20, v0
	v_mov_b32_e32 v21, v0
	v_mov_b32_e32 v22, v0
	v_mov_b32_e32 v23, v0
	v_mov_b32_e32 v32, v0
	v_mov_b32_e32 v33, v0
	v_mov_b32_e32 v34, v0
	v_mov_b32_e32 v35, v0
	v_mov_b32_e32 v36, v0
	v_mov_b32_e32 v37, v0
	v_mov_b32_e32 v38, v0
	v_mov_b32_e32 v39, v0
	v_mov_b32_e32 v48, v0
	v_mov_b32_e32 v49, v0
	v_mov_b32_e32 v50, v0
	v_mov_b32_e32 v51, v0
	v_mov_b32_e32 v52, v0
	v_mov_b32_e32 v53, v0
	v_mov_b32_e32 v54, v0
	v_mov_b32_e32 v55, v0
	v_mov_b32_e32 v8, v0
	v_mov_b32_e32 v9, v0
	v_mov_b32_e32 v10, v0
	v_mov_b32_e32 v11, v0
	v_mov_b32_e32 v12, v0
	v_mov_b32_e32 v13, v0
	v_mov_b32_e32 v14, v0
	v_mov_b32_e32 v15, v0
	v_mov_b32_e32 v24, v0
	v_mov_b32_e32 v25, v0
	v_mov_b32_e32 v26, v0
	v_mov_b32_e32 v27, v0
	v_mov_b32_e32 v28, v0
	v_mov_b32_e32 v29, v0
	v_mov_b32_e32 v30, v0
	v_mov_b32_e32 v31, v0
	v_mov_b32_e32 v40, v0
	v_mov_b32_e32 v41, v0
	v_mov_b32_e32 v42, v0
	v_mov_b32_e32 v43, v0
	v_mov_b32_e32 v44, v0
	v_mov_b32_e32 v45, v0
	v_mov_b32_e32 v46, v0
	v_mov_b32_e32 v47, v0
	v_mov_b32_e32 v56, v0
	v_mov_b32_e32 v57, v0
	v_mov_b32_e32 v58, v0
	v_mov_b32_e32 v59, v0
	v_mov_b32_e32 v60, v0
	v_mov_b32_e32 v61, v0
	v_mov_b32_e32 v62, v0
	v_mov_b32_e32 v63, v0
	v_mov_b32_e32 v64, v0
	v_mov_b32_e32 v65, v0
	v_mov_b32_e32 v66, v0
	v_mov_b32_e32 v67, v0
	v_mov_b32_e32 v68, v0
	v_mov_b32_e32 v69, v0
	v_mov_b32_e32 v70, v0
	v_mov_b32_e32 v71, v0
	v_mov_b32_e32 v80, v0
	v_mov_b32_e32 v81, v0
	v_mov_b32_e32 v82, v0
	v_mov_b32_e32 v83, v0
	v_mov_b32_e32 v84, v0
	v_mov_b32_e32 v85, v0
	v_mov_b32_e32 v86, v0
	v_mov_b32_e32 v87, v0
	v_mov_b32_e32 v96, v0
	v_mov_b32_e32 v97, v0
	v_mov_b32_e32 v98, v0
	v_mov_b32_e32 v99, v0
	v_mov_b32_e32 v100, v0
	v_mov_b32_e32 v101, v0
	v_mov_b32_e32 v102, v0
	v_mov_b32_e32 v103, v0
	v_mov_b32_e32 v112, v0
	v_mov_b32_e32 v113, v0
	v_mov_b32_e32 v114, v0
	v_mov_b32_e32 v115, v0
	v_mov_b32_e32 v116, v0
	v_mov_b32_e32 v117, v0
	v_mov_b32_e32 v118, v0
	v_mov_b32_e32 v119, v0
	v_mov_b32_e32 v72, v0
	v_mov_b32_e32 v73, v0
	v_mov_b32_e32 v74, v0
	v_mov_b32_e32 v75, v0
	v_mov_b32_e32 v76, v0
	v_mov_b32_e32 v77, v0
	v_mov_b32_e32 v78, v0
	v_mov_b32_e32 v79, v0
	v_mov_b32_e32 v88, v0
	v_mov_b32_e32 v89, v0
	v_mov_b32_e32 v90, v0
	v_mov_b32_e32 v91, v0
	v_mov_b32_e32 v92, v0
	v_mov_b32_e32 v93, v0
	v_mov_b32_e32 v94, v0
	v_mov_b32_e32 v95, v0
	v_mov_b32_e32 v104, v0
	v_mov_b32_e32 v105, v0
	v_mov_b32_e32 v106, v0
	v_mov_b32_e32 v107, v0
	v_mov_b32_e32 v108, v0
	v_mov_b32_e32 v109, v0
	v_mov_b32_e32 v110, v0
	v_mov_b32_e32 v111, v0
	v_mov_b32_e32 v120, v0
	v_mov_b32_e32 v121, v0
	v_mov_b32_e32 v122, v0
	v_mov_b32_e32 v123, v0
	v_mov_b32_e32 v124, v0
	v_mov_b32_e32 v125, v0
	v_mov_b32_e32 v126, v0
	v_mov_b32_e32 v127, v0
	v_readfirstlane_b32 s4, v182
	s_nop 3
	s_cmp_lt_u32 s4, 256
	s_cbranch_scc0 .Lkprio_1093
	s_setprio 1

.LBB0_1116:
	s_ashr_i32 s49, s48, 31
	s_lshl_b64 s[4:5], s[48:49], 18
	s_add_u32 s50, s30, s4
	s_addc_u32 s51, s60, s5
	s_and_b64 s[4:5], s[38:39], exec
	s_cselect_b32 s33, s51, s55
	s_cselect_b32 s36, s50, s54
	s_ashr_i32 s47, s46, 31
	s_lshl_b64 s[4:5], s[46:47], 18
	s_add_u32 s52, s61, s4
	s_addc_u32 s53, s62, s5
	s_and_b64 s[4:5], s[38:39], exec
	s_cselect_b32 s47, s53, s59
	s_cselect_b32 s49, s52, s58
	s_add_u32 s54, s54, 0x20080
	s_addc_u32 s55, s55, 0
	s_add_u32 s71, s58, 0x100
	v_mov_b32_e32 v0, 0
	s_addc_u32 s72, s59, 0
	s_mov_b32 s73, -2
	v_mov_b32_e32 v1, v0
	v_mov_b32_e32 v2, v0
	v_mov_b32_e32 v3, v0
	v_mov_b32_e32 v4, v0
	v_mov_b32_e32 v5, v0
	v_mov_b32_e32 v6, v0
	v_mov_b32_e32 v7, v0
	v_mov_b32_e32 v16, v0
	v_mov_b32_e32 v17, v0
	v_mov_b32_e32 v18, v0
	v_mov_b32_e32 v19, v0
	v_mov_b32_e32 v20, v0
	v_mov_b32_e32 v21, v0
	v_mov_b32_e32 v22, v0
	v_mov_b32_e32 v23, v0
	v_mov_b32_e32 v32, v0
	v_mov_b32_e32 v33, v0
	v_mov_b32_e32 v34, v0
	v_mov_b32_e32 v35, v0
	v_mov_b32_e32 v36, v0
	v_mov_b32_e32 v37, v0
	v_mov_b32_e32 v38, v0
	v_mov_b32_e32 v39, v0
	v_mov_b32_e32 v48, v0
	v_mov_b32_e32 v49, v0
	v_mov_b32_e32 v50, v0
	v_mov_b32_e32 v51, v0
	v_mov_b32_e32 v52, v0
	v_mov_b32_e32 v53, v0
	v_mov_b32_e32 v54, v0
	v_mov_b32_e32 v55, v0
	v_mov_b32_e32 v8, v0
	v_mov_b32_e32 v9, v0
	v_mov_b32_e32 v10, v0
	v_mov_b32_e32 v11, v0
	v_mov_b32_e32 v12, v0
	v_mov_b32_e32 v13, v0
	v_mov_b32_e32 v14, v0
	v_mov_b32_e32 v15, v0
	v_mov_b32_e32 v24, v0
	v_mov_b32_e32 v25, v0
	v_mov_b32_e32 v26, v0
	v_mov_b32_e32 v27, v0
	v_mov_b32_e32 v28, v0
	v_mov_b32_e32 v29, v0
	v_mov_b32_e32 v30, v0
	v_mov_b32_e32 v31, v0
	v_mov_b32_e32 v40, v0
	v_mov_b32_e32 v41, v0
	v_mov_b32_e32 v42, v0
	v_mov_b32_e32 v43, v0
	v_mov_b32_e32 v44, v0
	v_mov_b32_e32 v45, v0
	v_mov_b32_e32 v46, v0
	v_mov_b32_e32 v47, v0
	v_mov_b32_e32 v56, v0
	v_mov_b32_e32 v57, v0
	v_mov_b32_e32 v58, v0
	v_mov_b32_e32 v59, v0
	v_mov_b32_e32 v60, v0
	v_mov_b32_e32 v61, v0
	v_mov_b32_e32 v62, v0
	v_mov_b32_e32 v63, v0
	v_mov_b32_e32 v64, v0
	v_mov_b32_e32 v65, v0
	v_mov_b32_e32 v66, v0
	v_mov_b32_e32 v67, v0
	v_mov_b32_e32 v68, v0
	v_mov_b32_e32 v69, v0
	v_mov_b32_e32 v70, v0
	v_mov_b32_e32 v71, v0
	v_mov_b32_e32 v80, v0
	v_mov_b32_e32 v81, v0
	v_mov_b32_e32 v82, v0
	v_mov_b32_e32 v83, v0
	v_mov_b32_e32 v84, v0
	v_mov_b32_e32 v85, v0
	v_mov_b32_e32 v86, v0
	v_mov_b32_e32 v87, v0
	v_mov_b32_e32 v96, v0
	v_mov_b32_e32 v97, v0
	v_mov_b32_e32 v98, v0
	v_mov_b32_e32 v99, v0
	v_mov_b32_e32 v100, v0
	v_mov_b32_e32 v101, v0
	v_mov_b32_e32 v102, v0
	v_mov_b32_e32 v103, v0
	v_mov_b32_e32 v112, v0
	v_mov_b32_e32 v113, v0
	v_mov_b32_e32 v114, v0
	v_mov_b32_e32 v115, v0
	v_mov_b32_e32 v116, v0
	v_mov_b32_e32 v117, v0
	v_mov_b32_e32 v118, v0
	v_mov_b32_e32 v119, v0
	v_mov_b32_e32 v72, v0
	v_mov_b32_e32 v73, v0
	v_mov_b32_e32 v74, v0
	v_mov_b32_e32 v75, v0
	v_mov_b32_e32 v76, v0
	v_mov_b32_e32 v77, v0
	v_mov_b32_e32 v78, v0
	v_mov_b32_e32 v79, v0
	v_mov_b32_e32 v88, v0
	v_mov_b32_e32 v89, v0
	v_mov_b32_e32 v90, v0
	v_mov_b32_e32 v91, v0
	v_mov_b32_e32 v92, v0
	v_mov_b32_e32 v93, v0
	v_mov_b32_e32 v94, v0
	v_mov_b32_e32 v95, v0
	v_mov_b32_e32 v104, v0
	v_mov_b32_e32 v105, v0
	v_mov_b32_e32 v106, v0
	v_mov_b32_e32 v107, v0
	v_mov_b32_e32 v108, v0
	v_mov_b32_e32 v109, v0
	v_mov_b32_e32 v110, v0
	v_mov_b32_e32 v111, v0
	v_mov_b32_e32 v120, v0
	v_mov_b32_e32 v121, v0
	v_mov_b32_e32 v122, v0
	v_mov_b32_e32 v123, v0
	v_mov_b32_e32 v124, v0
	v_mov_b32_e32 v125, v0
	v_mov_b32_e32 v126, v0
	v_mov_b32_e32 v127, v0
	v_readfirstlane_b32 s4, v182
	s_nop 3
	s_cmp_lt_u32 s4, 256
	s_cbranch_scc0 .Lkprio_1117
	s_setprio 1

.LBB0_1206:
	s_ashr_i32 s53, s52, 31
	s_lshl_b64 s[4:5], s[52:53], 19
	s_add_u32 s3, s36, s4
	s_addc_u32 s28, s68, s5
	s_and_b64 s[4:5], s[42:43], exec
	s_cselect_b32 s55, s28, s61
	s_cselect_b32 s54, s3, s60
	s_ashr_i32 s51, s50, 31
	s_lshl_b64 s[4:5], s[50:51], 19
	s_add_u32 s3, s66, s4
	s_addc_u32 s28, s67, s5
	s_and_b64 s[4:5], s[42:43], exec
	s_cselect_b32 s59, s28, s63
	s_cselect_b32 s58, s3, s62
	s_add_u32 s3, s62, 0x100
	v_mov_b32_e32 v0, 0
	s_addc_u32 s28, s63, 0
	s_mov_b32 s29, -2
	s_waitcnt lgkmcnt(0)
	v_mov_b32_e32 v1, v0
	v_mov_b32_e32 v2, v0
	v_mov_b32_e32 v3, v0
	v_mov_b32_e32 v4, v0
	v_mov_b32_e32 v5, v0
	v_mov_b32_e32 v6, v0
	v_mov_b32_e32 v7, v0
	v_mov_b32_e32 v16, v0
	v_mov_b32_e32 v17, v0
	v_mov_b32_e32 v18, v0
	v_mov_b32_e32 v19, v0
	v_mov_b32_e32 v20, v0
	v_mov_b32_e32 v21, v0
	v_mov_b32_e32 v22, v0
	v_mov_b32_e32 v23, v0
	v_mov_b32_e32 v32, v0
	v_mov_b32_e32 v33, v0
	v_mov_b32_e32 v34, v0
	v_mov_b32_e32 v35, v0
	v_mov_b32_e32 v36, v0
	v_mov_b32_e32 v37, v0
	v_mov_b32_e32 v38, v0
	v_mov_b32_e32 v39, v0
	v_mov_b32_e32 v48, v0
	v_mov_b32_e32 v49, v0
	v_mov_b32_e32 v50, v0
	v_mov_b32_e32 v51, v0
	v_mov_b32_e32 v52, v0
	v_mov_b32_e32 v53, v0
	v_mov_b32_e32 v54, v0
	v_mov_b32_e32 v55, v0
	v_mov_b32_e32 v8, v0
	v_mov_b32_e32 v9, v0
	v_mov_b32_e32 v10, v0
	v_mov_b32_e32 v11, v0
	v_mov_b32_e32 v12, v0
	v_mov_b32_e32 v13, v0
	v_mov_b32_e32 v14, v0
	v_mov_b32_e32 v15, v0
	v_mov_b32_e32 v24, v0
	v_mov_b32_e32 v25, v0
	v_mov_b32_e32 v26, v0
	v_mov_b32_e32 v27, v0
	v_mov_b32_e32 v28, v0
	v_mov_b32_e32 v29, v0
	v_mov_b32_e32 v30, v0
	v_mov_b32_e32 v31, v0
	v_mov_b32_e32 v40, v0
	v_mov_b32_e32 v41, v0
	v_mov_b32_e32 v42, v0
	v_mov_b32_e32 v43, v0
	v_mov_b32_e32 v44, v0
	v_mov_b32_e32 v45, v0
	v_mov_b32_e32 v46, v0
	v_mov_b32_e32 v47, v0
	v_mov_b32_e32 v56, v0
	v_mov_b32_e32 v57, v0
	v_mov_b32_e32 v58, v0
	v_mov_b32_e32 v59, v0
	v_mov_b32_e32 v60, v0
	v_mov_b32_e32 v61, v0
	v_mov_b32_e32 v62, v0
	v_mov_b32_e32 v63, v0
	v_mov_b32_e32 v64, v0
	v_mov_b32_e32 v65, v0
	v_mov_b32_e32 v66, v0
	v_mov_b32_e32 v67, v0
	v_mov_b32_e32 v68, v0
	v_mov_b32_e32 v69, v0
	v_mov_b32_e32 v70, v0
	v_mov_b32_e32 v71, v0
	v_mov_b32_e32 v80, v0
	v_mov_b32_e32 v81, v0
	v_mov_b32_e32 v82, v0
	v_mov_b32_e32 v83, v0
	v_mov_b32_e32 v84, v0
	v_mov_b32_e32 v85, v0
	v_mov_b32_e32 v86, v0
	v_mov_b32_e32 v87, v0
	v_mov_b32_e32 v96, v0
	v_mov_b32_e32 v97, v0
	v_mov_b32_e32 v98, v0
	v_mov_b32_e32 v99, v0
	v_mov_b32_e32 v100, v0
	v_mov_b32_e32 v101, v0
	v_mov_b32_e32 v102, v0
	v_mov_b32_e32 v103, v0
	v_mov_b32_e32 v112, v0
	v_mov_b32_e32 v113, v0
	v_mov_b32_e32 v114, v0
	v_mov_b32_e32 v115, v0
	v_mov_b32_e32 v116, v0
	v_mov_b32_e32 v117, v0
	v_mov_b32_e32 v118, v0
	v_mov_b32_e32 v119, v0
	v_mov_b32_e32 v72, v0
	v_mov_b32_e32 v73, v0
	v_mov_b32_e32 v74, v0
	v_mov_b32_e32 v75, v0
	v_mov_b32_e32 v76, v0
	v_mov_b32_e32 v77, v0
	v_mov_b32_e32 v78, v0
	v_mov_b32_e32 v79, v0
	v_mov_b32_e32 v88, v0
	v_mov_b32_e32 v89, v0
	v_mov_b32_e32 v90, v0
	v_mov_b32_e32 v91, v0
	v_mov_b32_e32 v92, v0
	v_mov_b32_e32 v93, v0
	v_mov_b32_e32 v94, v0
	v_mov_b32_e32 v95, v0
	v_mov_b32_e32 v104, v0
	v_mov_b32_e32 v105, v0
	v_mov_b32_e32 v106, v0
	v_mov_b32_e32 v107, v0
	v_mov_b32_e32 v108, v0
	v_mov_b32_e32 v109, v0
	v_mov_b32_e32 v110, v0
	v_mov_b32_e32 v111, v0
	v_mov_b32_e32 v120, v0
	v_mov_b32_e32 v121, v0
	v_mov_b32_e32 v122, v0
	v_mov_b32_e32 v123, v0
	v_mov_b32_e32 v124, v0
	v_mov_b32_e32 v125, v0
	v_mov_b32_e32 v126, v0
	v_mov_b32_e32 v127, v0
	v_readfirstlane_b32 s4, v182
	s_nop 3
	s_cmp_lt_u32 s4, 256
	s_cbranch_scc0 .Lkprio_1207
	s_setprio 1

.LBB0_1304:
	s_ashr_i32 s51, s50, 31
	s_lshl_b64 s[2:3], s[50:51], 19
	s_add_u32 s52, s28, s2
	s_addc_u32 s53, s29, s3
	s_and_b64 s[2:3], s[38:39], exec
	s_cselect_b32 s36, s53, s35
	s_cselect_b32 s51, s52, s34
	s_ashr_i32 s49, s48, 31
	s_lshl_b64 s[2:3], s[48:49], 19
	s_add_u32 s54, s30, s2
	s_addc_u32 s55, s62, s3
	s_and_b64 s[2:3], s[38:39], exec
	s_cselect_b32 s49, s55, s61
	s_cselect_b32 s70, s54, s60
	s_add_u32 s2, s34, 0x40080
	s_addc_u32 s3, s35, 0
	s_add_u32 s71, s60, 0x100
	v_mov_b32_e32 v0, 0
	s_addc_u32 s72, s61, 0
	s_mov_b32 s73, -2
	v_mov_b32_e32 v1, v0
	v_mov_b32_e32 v2, v0
	v_mov_b32_e32 v3, v0
	v_mov_b32_e32 v4, v0
	v_mov_b32_e32 v5, v0
	v_mov_b32_e32 v6, v0
	v_mov_b32_e32 v7, v0
	v_mov_b32_e32 v16, v0
	v_mov_b32_e32 v17, v0
	v_mov_b32_e32 v18, v0
	v_mov_b32_e32 v19, v0
	v_mov_b32_e32 v20, v0
	v_mov_b32_e32 v21, v0
	v_mov_b32_e32 v22, v0
	v_mov_b32_e32 v23, v0
	v_mov_b32_e32 v32, v0
	v_mov_b32_e32 v33, v0
	v_mov_b32_e32 v34, v0
	v_mov_b32_e32 v35, v0
	v_mov_b32_e32 v36, v0
	v_mov_b32_e32 v37, v0
	v_mov_b32_e32 v38, v0
	v_mov_b32_e32 v39, v0
	v_mov_b32_e32 v48, v0
	v_mov_b32_e32 v49, v0
	v_mov_b32_e32 v50, v0
	v_mov_b32_e32 v51, v0
	v_mov_b32_e32 v52, v0
	v_mov_b32_e32 v53, v0
	v_mov_b32_e32 v54, v0
	v_mov_b32_e32 v55, v0
	v_mov_b32_e32 v8, v0
	v_mov_b32_e32 v9, v0
	v_mov_b32_e32 v10, v0
	v_mov_b32_e32 v11, v0
	v_mov_b32_e32 v12, v0
	v_mov_b32_e32 v13, v0
	v_mov_b32_e32 v14, v0
	v_mov_b32_e32 v15, v0
	v_mov_b32_e32 v24, v0
	v_mov_b32_e32 v25, v0
	v_mov_b32_e32 v26, v0
	v_mov_b32_e32 v27, v0
	v_mov_b32_e32 v28, v0
	v_mov_b32_e32 v29, v0
	v_mov_b32_e32 v30, v0
	v_mov_b32_e32 v31, v0
	v_mov_b32_e32 v40, v0
	v_mov_b32_e32 v41, v0
	v_mov_b32_e32 v42, v0
	v_mov_b32_e32 v43, v0
	v_mov_b32_e32 v44, v0
	v_mov_b32_e32 v45, v0
	v_mov_b32_e32 v46, v0
	v_mov_b32_e32 v47, v0
	v_mov_b32_e32 v56, v0
	v_mov_b32_e32 v57, v0
	v_mov_b32_e32 v58, v0
	v_mov_b32_e32 v59, v0
	v_mov_b32_e32 v60, v0
	v_mov_b32_e32 v61, v0
	v_mov_b32_e32 v62, v0
	v_mov_b32_e32 v63, v0
	v_mov_b32_e32 v64, v0
	v_mov_b32_e32 v65, v0
	v_mov_b32_e32 v66, v0
	v_mov_b32_e32 v67, v0
	v_mov_b32_e32 v68, v0
	v_mov_b32_e32 v69, v0
	v_mov_b32_e32 v70, v0
	v_mov_b32_e32 v71, v0
	v_mov_b32_e32 v80, v0
	v_mov_b32_e32 v81, v0
	v_mov_b32_e32 v82, v0
	v_mov_b32_e32 v83, v0
	v_mov_b32_e32 v84, v0
	v_mov_b32_e32 v85, v0
	v_mov_b32_e32 v86, v0
	v_mov_b32_e32 v87, v0
	v_mov_b32_e32 v96, v0
	v_mov_b32_e32 v97, v0
	v_mov_b32_e32 v98, v0
	v_mov_b32_e32 v99, v0
	v_mov_b32_e32 v100, v0
	v_mov_b32_e32 v101, v0
	v_mov_b32_e32 v102, v0
	v_mov_b32_e32 v103, v0
	v_mov_b32_e32 v112, v0
	v_mov_b32_e32 v113, v0
	v_mov_b32_e32 v114, v0
	v_mov_b32_e32 v115, v0
	v_mov_b32_e32 v116, v0
	v_mov_b32_e32 v117, v0
	v_mov_b32_e32 v118, v0
	v_mov_b32_e32 v119, v0
	v_mov_b32_e32 v72, v0
	v_mov_b32_e32 v73, v0
	v_mov_b32_e32 v74, v0
	v_mov_b32_e32 v75, v0
	v_mov_b32_e32 v76, v0
	v_mov_b32_e32 v77, v0
	v_mov_b32_e32 v78, v0
	v_mov_b32_e32 v79, v0
	v_mov_b32_e32 v88, v0
	v_mov_b32_e32 v89, v0
	v_mov_b32_e32 v90, v0
	v_mov_b32_e32 v91, v0
	v_mov_b32_e32 v92, v0
	v_mov_b32_e32 v93, v0
	v_mov_b32_e32 v94, v0
	v_mov_b32_e32 v95, v0
	v_mov_b32_e32 v104, v0
	v_mov_b32_e32 v105, v0
	v_mov_b32_e32 v106, v0
	v_mov_b32_e32 v107, v0
	v_mov_b32_e32 v108, v0
	v_mov_b32_e32 v109, v0
	v_mov_b32_e32 v110, v0
	v_mov_b32_e32 v111, v0
	v_mov_b32_e32 v120, v0
	v_mov_b32_e32 v121, v0
	v_mov_b32_e32 v122, v0
	v_mov_b32_e32 v123, v0
	v_mov_b32_e32 v124, v0
	v_mov_b32_e32 v125, v0
	v_mov_b32_e32 v126, v0
	v_mov_b32_e32 v127, v0
	v_readfirstlane_b32 s4, v182
	s_nop 3
	s_cmp_lt_u32 s4, 256
	s_cbranch_scc0 .Lkprio_1305
	s_setprio 1

.LBB0_1398:
	s_add_u32 s3, s58, 0x100
	v_mov_b32_e32 v0, 0
	s_addc_u32 s28, s59, 0
	s_mov_b32 s29, -2
	s_waitcnt lgkmcnt(0)
	v_mov_b32_e32 v1, v0
	v_mov_b32_e32 v2, v0
	v_mov_b32_e32 v3, v0
	v_mov_b32_e32 v4, v0
	v_mov_b32_e32 v5, v0
	v_mov_b32_e32 v6, v0
	v_mov_b32_e32 v7, v0
	v_mov_b32_e32 v16, v0
	v_mov_b32_e32 v17, v0
	v_mov_b32_e32 v18, v0
	v_mov_b32_e32 v19, v0
	v_mov_b32_e32 v20, v0
	v_mov_b32_e32 v21, v0
	v_mov_b32_e32 v22, v0
	v_mov_b32_e32 v23, v0
	v_mov_b32_e32 v32, v0
	v_mov_b32_e32 v33, v0
	v_mov_b32_e32 v34, v0
	v_mov_b32_e32 v35, v0
	v_mov_b32_e32 v36, v0
	v_mov_b32_e32 v37, v0
	v_mov_b32_e32 v38, v0
	v_mov_b32_e32 v39, v0
	v_mov_b32_e32 v48, v0
	v_mov_b32_e32 v49, v0
	v_mov_b32_e32 v50, v0
	v_mov_b32_e32 v51, v0
	v_mov_b32_e32 v52, v0
	v_mov_b32_e32 v53, v0
	v_mov_b32_e32 v54, v0
	v_mov_b32_e32 v55, v0
	v_mov_b32_e32 v8, v0
	v_mov_b32_e32 v9, v0
	v_mov_b32_e32 v10, v0
	v_mov_b32_e32 v11, v0
	v_mov_b32_e32 v12, v0
	v_mov_b32_e32 v13, v0
	v_mov_b32_e32 v14, v0
	v_mov_b32_e32 v15, v0
	v_mov_b32_e32 v24, v0
	v_mov_b32_e32 v25, v0
	v_mov_b32_e32 v26, v0
	v_mov_b32_e32 v27, v0
	v_mov_b32_e32 v28, v0
	v_mov_b32_e32 v29, v0
	v_mov_b32_e32 v30, v0
	v_mov_b32_e32 v31, v0
	v_mov_b32_e32 v40, v0
	v_mov_b32_e32 v41, v0
	v_mov_b32_e32 v42, v0
	v_mov_b32_e32 v43, v0
	v_mov_b32_e32 v44, v0
	v_mov_b32_e32 v45, v0
	v_mov_b32_e32 v46, v0
	v_mov_b32_e32 v47, v0
	v_mov_b32_e32 v56, v0
	v_mov_b32_e32 v57, v0
	v_mov_b32_e32 v58, v0
	v_mov_b32_e32 v59, v0
	v_mov_b32_e32 v60, v0
	v_mov_b32_e32 v61, v0
	v_mov_b32_e32 v62, v0
	v_mov_b32_e32 v63, v0
	v_mov_b32_e32 v64, v0
	v_mov_b32_e32 v65, v0
	v_mov_b32_e32 v66, v0
	v_mov_b32_e32 v67, v0
	v_mov_b32_e32 v68, v0
	v_mov_b32_e32 v69, v0
	v_mov_b32_e32 v70, v0
	v_mov_b32_e32 v71, v0
	v_mov_b32_e32 v80, v0
	v_mov_b32_e32 v81, v0
	v_mov_b32_e32 v82, v0
	v_mov_b32_e32 v83, v0
	v_mov_b32_e32 v84, v0
	v_mov_b32_e32 v85, v0
	v_mov_b32_e32 v86, v0
	v_mov_b32_e32 v87, v0
	v_mov_b32_e32 v96, v0
	v_mov_b32_e32 v97, v0
	v_mov_b32_e32 v98, v0
	v_mov_b32_e32 v99, v0
	v_mov_b32_e32 v100, v0
	v_mov_b32_e32 v101, v0
	v_mov_b32_e32 v102, v0
	v_mov_b32_e32 v103, v0
	v_mov_b32_e32 v112, v0
	v_mov_b32_e32 v113, v0
	v_mov_b32_e32 v114, v0
	v_mov_b32_e32 v115, v0
	v_mov_b32_e32 v116, v0
	v_mov_b32_e32 v117, v0
	v_mov_b32_e32 v118, v0
	v_mov_b32_e32 v119, v0
	v_mov_b32_e32 v72, v0
	v_mov_b32_e32 v73, v0
	v_mov_b32_e32 v74, v0
	v_mov_b32_e32 v75, v0
	v_mov_b32_e32 v76, v0
	v_mov_b32_e32 v77, v0
	v_mov_b32_e32 v78, v0
	v_mov_b32_e32 v79, v0
	v_mov_b32_e32 v88, v0
	v_mov_b32_e32 v89, v0
	v_mov_b32_e32 v90, v0
	v_mov_b32_e32 v91, v0
	v_mov_b32_e32 v92, v0
	v_mov_b32_e32 v93, v0
	v_mov_b32_e32 v94, v0
	v_mov_b32_e32 v95, v0
	v_mov_b32_e32 v104, v0
	v_mov_b32_e32 v105, v0
	v_mov_b32_e32 v106, v0
	v_mov_b32_e32 v107, v0
	v_mov_b32_e32 v108, v0
	v_mov_b32_e32 v109, v0
	v_mov_b32_e32 v110, v0
	v_mov_b32_e32 v111, v0
	v_mov_b32_e32 v120, v0
	v_mov_b32_e32 v121, v0
	v_mov_b32_e32 v122, v0
	v_mov_b32_e32 v123, v0
	v_mov_b32_e32 v124, v0
	v_mov_b32_e32 v125, v0
	v_mov_b32_e32 v126, v0
	v_mov_b32_e32 v127, v0
	v_readfirstlane_b32 s4, v182
	s_nop 3
	s_cmp_lt_u32 s4, 256
	s_cbranch_scc0 .Lkprio_1399
	s_setprio 1
